# v13 + FFN-in fast path stages C above the A buffers and DMA-prefetches the next tile A operand (k-tiles 0,1) during the epilogue
# baseline (speedup 1.0000x reference)
; template <int MODE>
; DI void gemm_epilogue(const float* Cs, int m0, int n0, const Epi& ep) {
;     ...
;         const int mt = m0 >> 7, ch0 = (n0 >> 7) * 64, c8 = (tid & 7) * 8, ch = ch0 + c8;
;         const float* cw = ep.c0;
;         const F8 w0 = ldf8(cw + ch), w1 = ldf8(cw + 2816 + ch), w2 = ldf8(cw + 2 * 2816 + ch);
;         const bool defer01 = (m0 < MP) && ((m0 & 8191) != 0);
; #pragma unroll
;         for (int it = 0; it < 2; ++it) {
;             const int i = (tid >> 3) + 64 * it, r = m0 + i;
;             int sq, pos, len; rowinfo(r, sq, pos, len);
;             const F8 g0 = ldf8(Cs + i * LDC + c8), up = ldf8(Cs + i * LDC + 64 + c8);
;             if (i >= 126) stf8(ep.f0 + ((size_t)mt * 2 + (i - 126)) * 2816 + ch, g0);
;             if (i < 2) { stf8(ep.f1 + ((size_t)mt * 2 + i) * 2816 + ch, g0); stf8(ep.f2 + ((size_t)mt * 2 + i) * 2816 + ch, up); }
;             if (pos >= len - 2) {
;                 float* so = sq < 4 ? ep.out + O_PFF + (((size_t)ep.layer * 4 + sq) * 2 + (pos - (len - 2))) * 2816
;                                    : ep.out + O_SFF + (((size_t)ep.layer * 8 + (sq - 4)) * 2 + (pos - (len - 2))) * 2816;
;                 stf8(so + ch, g0);
;             }
;             if (i < 2 && defer01) continue;
;             F8 g1, g2;
;             const float* hist = sq >= 4 ? ep.c1 + ((size_t)ep.layer * 8 + (sq - 4)) * 2 * 2816 + ch : nullptr;
;             if (pos >= 1) g1 = ldf8(Cs + (i - 1) * LDC + c8);
;             else if (hist) g1 = ldf8(hist + 2816);
;             else { for (int e = 0; e < 8; ++e) g1.v[e] = 0.f; }
;             if (pos >= 2) g2 = ldf8(Cs + (i - 2) * LDC + c8);
;             else if (hist) g2 = ldf8(hist + (size_t)pos * 2816);
;             else { for (int e = 0; e < 8; ++e) g2.v[e] = 0.f; }
;             F8 o;
; #pragma unroll
;             for (int e = 0; e < 8; ++e) o.v[e] = siluf(w0.v[e] * g2.v[e] + w1.v[e] * g1.v[e] + w2.v[e] * g0.v[e]) * up.v[e];
;             stb8(ep.b0 + (size_t)r * 2816 + ch, o);
; template <int MODE>
; DI void gemm_phase(const bf16_t* __restrict__ A, const bf16_t* __restrict__ Bt, int M, int N, int K, const Epi& ep) {
;     ...
;         { const int q = nwg / NXCD, r = nwg % NXCD, xcd = wgid % NXCD, off = wgid / NXCD; wgid = (xcd < r ? xcd * (q + 1) : r * (q + 1) + (xcd - r) * q) + off; }
;         const int nig = WGM * nN, gid = wgid / nig, fm = gid * WGM, gsz = min(nM - fm, WGM);
.Lffn_fast:
	s_lshl_b32 s54, s27, 8
	s_lshl_b32 s30, s26, 7
	s_lshl_b32 s31, s27, 2
	v_lshrrev_b32_e32 v195, 3, v250
	v_and_b32_e32 v212, 7, v250
	v_lshlrev_b32_e32 v212, 3, v212
	v_add_u32_e32 v64, s30, v212
	v_add_u32_e32 v65, s54, v195
	s_movk_i32 s0, 0x1600
	v_add_u32_e32 v66, s31, v195
	v_mul_lo_u32 v65, v65, s0
	v_mul_lo_u32 v66, v66, s3
	v_mul_u32_u24_e32 v197, 0x210, v195
	v_lshl_add_u32 v65, v64, 1, v65
	v_lshlrev_b32_e32 v64, 2, v64
	v_lshl_add_u32 v67, v212, 2, 16
	v_add_u32_e32 v66, v66, v64
	v_add_u32_e32 v197, v197, v67
	v_cmp_lt_u32_e64 s[40:41], 1, v195
	v_cmp_gt_u32_e64 s[42:43], 2, v195
	v_cmp_lt_u32_e64 s[44:45], 61, v195
	v_add_u32_e32 v196, 0xfffffbe0, v197
	v_max_i32_e32 v196, v196, v67
	v_add_u32_e32 v156, 0x10000, v194
	v_add_u32_e32 v157, 0x10000, v196
	v_add_u32_e32 v158, 0x10000, v197
	global_load_dwordx4 v[128:131], v64, s[6:7] offset:0
	global_load_dwordx4 v[132:135], v64, s[6:7] offset:16
	global_load_dwordx4 v[136:139], v64, s[14:15] offset:0
	global_load_dwordx4 v[140:143], v64, s[14:15] offset:16
	global_load_dwordx4 v[144:147], v64, s[18:19] offset:0
	global_load_dwordx4 v[148:151], v64, s[18:19] offset:16
	s_add_i32 s0, s48, 1
	s_mul_i32 s0, s0, s46
	s_add_i32 s0, s0, s47
	s_cmpk_ge_i32 s0, 0xb2c
	s_cbranch_scc1 .Lffn_nopf
	s_and_b32 s1, s0, 7
	s_lshr_b32 s0, s0, 3
	s_mul_i32 s30, s1, 0x166
	s_mul_i32 s31, s1, 0x165
	s_add_i32 s31, s31, 4
	s_cmp_gt_u32 s1, 3
	s_cselect_b32 s30, s31, s30
	s_add_i32 s0, s0, s30
	s_mul_hi_i32 s1, s0, 0x2e8ba2e9
	s_lshr_b32 s30, s1, 31
	s_ashr_i32 s1, s1, 5
	s_add_i32 s1, s1, s30
	s_mul_i32 s30, s1, 0xb0
	s_sub_i32 s0, s0, s30
	s_lshl_b32 s1, s1, 3
	s_sub_i32 s30, 0x82, s1
	s_min_u32 s30, s30, 8
	s_add_i32 s30, s30, -1
	s_and_b32 s0, s0, s30
	s_add_i32 s0, s0, s1
	s_lshl_b32 s0, s0, 19
	s_or_b32 s1, s0, 0x40000
	s_or_b32 s30, s0, 0x80
	s_or_b32 s31, s0, 0x40080
	v_readfirstlane_b32 s54, v174
	s_mov_b32 m0, s54
	v_readfirstlane_b32 s54, v175
	buffer_load_dwordx4 v168, s[8:11], s0 offen lds
	s_mov_b32 m0, s54
	s_nop 0
	buffer_load_dwordx4 v169, s[8:11], s0 offen lds
	v_readfirstlane_b32 s54, v176
	s_mov_b32 m0, s54
	v_readfirstlane_b32 s54, v177
	buffer_load_dwordx4 v168, s[8:11], s1 offen lds
	s_mov_b32 m0, s54
	s_nop 0
	buffer_load_dwordx4 v169, s[8:11], s1 offen lds
	v_readfirstlane_b32 s54, v180
	s_mov_b32 m0, s54
	v_readfirstlane_b32 s54, v181
	buffer_load_dwordx4 v168, s[8:11], s30 offen lds
	s_mov_b32 m0, s54
	s_nop 0
	buffer_load_dwordx4 v169, s[8:11], s30 offen lds
	v_readfirstlane_b32 s54, v184
	s_mov_b32 m0, s54
	v_readfirstlane_b32 s54, v185
	buffer_load_dwordx4 v168, s[8:11], s31 offen lds
	s_mov_b32 m0, s54
	s_nop 0
	buffer_load_dwordx4 v169, s[8:11], s31 offen lds
	s_branch .Lffn_pfdone

; DI void stf8(float* p, const F8& f) { *(float4*)p = make_float4(f.v[0], f.v[1], f.v[2], f.v[3]); *(float4*)(p + 4) = make_float4(f.v[4], f.v[5], f.v[6], f.v[7]); }
; DI void stb8(bf16_t* p, const F8& f) { *(uint4*)p = pack8(f); }
; DI float siluf(float x) { return x / (1.f + __expf(-x)); }
; template <int MODE>
; DI void gemm_epilogue(const float* Cs, int m0, int n0, const Epi& ep) {
;     ...
;         const int mt = m0 >> 7, ch0 = (n0 >> 7) * 64, c8 = (tid & 7) * 8, ch = ch0 + c8;
;         const float* cw = ep.c0;
;         const F8 w0 = ldf8(cw + ch), w1 = ldf8(cw + 2816 + ch), w2 = ldf8(cw + 2 * 2816 + ch);
;         const bool defer01 = (m0 < MP) && ((m0 & 8191) != 0);
; #pragma unroll
;         for (int it = 0; it < 2; ++it) {
;             const int i = (tid >> 3) + 64 * it, r = m0 + i;
;             int sq, pos, len; rowinfo(r, sq, pos, len);
;             const F8 g0 = ldf8(Cs + i * LDC + c8), up = ldf8(Cs + i * LDC + 64 + c8);
;             if (i >= 126) stf8(ep.f0 + ((size_t)mt * 2 + (i - 126)) * 2816 + ch, g0);
;             if (i < 2) { stf8(ep.f1 + ((size_t)mt * 2 + i) * 2816 + ch, g0); stf8(ep.f2 + ((size_t)mt * 2 + i) * 2816 + ch, up); }
;             if (pos >= len - 2) {
;                 float* so = sq < 4 ? ep.out + O_PFF + (((size_t)ep.layer * 4 + sq) * 2 + (pos - (len - 2))) * 2816
;                                    : ep.out + O_SFF + (((size_t)ep.layer * 8 + (sq - 4)) * 2 + (pos - (len - 2))) * 2816;
;                 stf8(so + ch, g0);
;             }
;             if (i < 2 && defer01) continue;
;             F8 g1, g2;
;             const float* hist = sq >= 4 ? ep.c1 + ((size_t)ep.layer * 8 + (sq - 4)) * 2 * 2816 + ch : nullptr;
;             if (pos >= 1) g1 = ldf8(Cs + (i - 1) * LDC + c8);
;             else if (hist) g1 = ldf8(hist + 2816);
;             else { for (int e = 0; e < 8; ++e) g1.v[e] = 0.f; }
;             if (pos >= 2) g2 = ldf8(Cs + (i - 2) * LDC + c8);
;             else if (hist) g2 = ldf8(hist + (size_t)pos * 2816);
;             else { for (int e = 0; e < 8; ++e) g2.v[e] = 0.f; }
;             F8 o;
; #pragma unroll
;             for (int e = 0; e < 8; ++e) o.v[e] = siluf(w0.v[e] * g2.v[e] + w1.v[e] * g1.v[e] + w2.v[e] * g0.v[e]) * up.v[e];
;             stb8(ep.b0 + (size_t)r * 2816 + ch, o);
.Lffn_pfdone:
	s_mov_b32 s30, 0xbfb8aa3b
	s_mov_b32 s31, 0xbfb8aa3b
	ds_write_b128 v156, v[96:99]
	ds_write_b128 v156, v[100:103] offset:64
	ds_write_b128 v156, v[104:107] offset:8448
	ds_write_b128 v156, v[108:111] offset:8512
	ds_write_b128 v156, v[112:115] offset:16896
	ds_write_b128 v156, v[116:119] offset:16960
	ds_write_b128 v156, v[120:123] offset:25344
	ds_write_b128 v156, v[124:127] offset:25408
	s_waitcnt lgkmcnt(0)
	s_barrier
	ds_read_b128 v[96:99], v158
	ds_read_b128 v[100:103], v158 offset:16
	ds_read_b128 v[104:107], v158 offset:256
	ds_read_b128 v[108:111], v158 offset:272
	ds_read_b128 v[112:115], v157 offset:528
	ds_read_b128 v[116:119], v157 offset:544
	ds_read_b128 v[120:123], v157
	ds_read_b128 v[124:127], v157 offset:16
	s_waitcnt vmcnt(8)
	s_mov_b64 exec, s[42:43]
	s_cbranch_execz .Lffn_f1
	s_waitcnt lgkmcnt(4)
	global_store_dwordx4 v66, v[96:99], s[80:81] offset:0
	global_store_dwordx4 v66, v[100:103], s[80:81] offset:16
	global_store_dwordx4 v66, v[104:107], s[82:83] offset:0
	global_store_dwordx4 v66, v[108:111], s[82:83] offset:16
.Lffn_f1:
	s_mov_b64 exec, -1
	s_waitcnt lgkmcnt(0)
	v_pk_mul_f32 v[120:121], v[128:129], v[120:121]
	v_pk_mul_f32 v[122:123], v[130:131], v[122:123]
	v_pk_mul_f32 v[124:125], v[132:133], v[124:125]
	v_pk_mul_f32 v[126:127], v[134:135], v[126:127]
	v_pk_fma_f32 v[120:121], v[136:137], v[112:113], v[120:121]
	v_pk_fma_f32 v[122:123], v[138:139], v[114:115], v[122:123]
	v_pk_fma_f32 v[124:125], v[140:141], v[116:117], v[124:125]
	v_pk_fma_f32 v[126:127], v[142:143], v[118:119], v[126:127]
	v_pk_fma_f32 v[120:121], v[144:145], v[96:97], v[120:121]
	v_pk_fma_f32 v[122:123], v[146:147], v[98:99], v[122:123]
	v_pk_fma_f32 v[124:125], v[148:149], v[100:101], v[124:125]
	v_pk_fma_f32 v[126:127], v[150:151], v[102:103], v[126:127]
	v_pk_mul_f32 v[152:153], v[120:121], s[30:31]
	v_pk_mul_f32 v[154:155], v[122:123], s[30:31]
	v_pk_mul_f32 v[164:165], v[124:125], s[30:31]
	v_pk_mul_f32 v[166:167], v[126:127], s[30:31]
	v_pk_mul_f32 v[120:121], v[104:105], v[120:121]
	v_pk_mul_f32 v[122:123], v[106:107], v[122:123]
	v_pk_mul_f32 v[124:125], v[108:109], v[124:125]
	v_pk_mul_f32 v[126:127], v[110:111], v[126:127]
	v_exp_f32_e32 v152, v152
	v_exp_f32_e32 v153, v153
	v_exp_f32_e32 v154, v154
	v_exp_f32_e32 v155, v155
	v_exp_f32_e32 v164, v164
	v_exp_f32_e32 v165, v165
	v_exp_f32_e32 v166, v166
	v_exp_f32_e32 v167, v167
	v_pk_add_f32 v[152:153], v[152:153], 1.0 op_sel_hi:[1,0]
	v_pk_add_f32 v[154:155], v[154:155], 1.0 op_sel_hi:[1,0]
	v_pk_add_f32 v[164:165], v[164:165], 1.0 op_sel_hi:[1,0]
	v_pk_add_f32 v[166:167], v[166:167], 1.0 op_sel_hi:[1,0]
	v_rcp_f32_e32 v152, v152
	v_rcp_f32_e32 v153, v153
	v_rcp_f32_e32 v154, v154
	v_rcp_f32_e32 v155, v155
	v_rcp_f32_e32 v164, v164
	v_rcp_f32_e32 v165, v165
	v_rcp_f32_e32 v166, v166
	v_rcp_f32_e32 v167, v167
	v_pk_mul_f32 v[120:121], v[120:121], v[152:153]
	v_pk_mul_f32 v[122:123], v[122:123], v[154:155]
	v_pk_mul_f32 v[124:125], v[124:125], v[164:165]
	v_pk_mul_f32 v[126:127], v[126:127], v[166:167]
	v_cvt_pk_bf16_f32 v152, v120, v121
	v_cvt_pk_bf16_f32 v153, v122, v123
	v_cvt_pk_bf16_f32 v154, v124, v125
	v_cvt_pk_bf16_f32 v155, v126, v127
	s_mov_b64 exec, s[40:41]
	global_store_dwordx4 v65, v[152:155], s[84:85] offset:0
	s_mov_b64 exec, -1
	ds_read_b128 v[96:99], v158 offset:33792
	ds_read_b128 v[100:103], v158 offset:33808
	ds_read_b128 v[104:107], v158 offset:34048
	ds_read_b128 v[108:111], v158 offset:34064
	ds_read_b128 v[112:115], v158 offset:33264
	ds_read_b128 v[116:119], v158 offset:33280
	ds_read_b128 v[120:123], v158 offset:32736
	ds_read_b128 v[124:127], v158 offset:32752
	v_add_u32_e32 v67, 0x58000, v65
	s_mov_b64 exec, s[44:45]
	s_cbranch_execz .Lffn_f2
	v_add_u32_e32 v212, 0xfff55800, v66
	s_waitcnt lgkmcnt(6)
	global_store_dwordx4 v212, v[96:99], s[72:73] offset:0
	global_store_dwordx4 v212, v[100:103], s[72:73] offset:16
.Lffn_f2:
	s_mov_b64 exec, -1
	s_waitcnt lgkmcnt(0)
	v_pk_mul_f32 v[120:121], v[128:129], v[120:121]
	v_pk_mul_f32 v[122:123], v[130:131], v[122:123]
	v_pk_mul_f32 v[124:125], v[132:133], v[124:125]
	v_pk_mul_f32 v[126:127], v[134:135], v[126:127]
	v_pk_fma_f32 v[120:121], v[136:137], v[112:113], v[120:121]
	v_pk_fma_f32 v[122:123], v[138:139], v[114:115], v[122:123]
	v_pk_fma_f32 v[124:125], v[140:141], v[116:117], v[124:125]
	v_pk_fma_f32 v[126:127], v[142:143], v[118:119], v[126:127]
	v_pk_fma_f32 v[120:121], v[144:145], v[96:97], v[120:121]
	v_pk_fma_f32 v[122:123], v[146:147], v[98:99], v[122:123]
	v_pk_fma_f32 v[124:125], v[148:149], v[100:101], v[124:125]
	v_pk_fma_f32 v[126:127], v[150:151], v[102:103], v[126:127]
	v_pk_mul_f32 v[152:153], v[120:121], s[30:31]
	v_pk_mul_f32 v[154:155], v[122:123], s[30:31]
	v_pk_mul_f32 v[164:165], v[124:125], s[30:31]
	v_pk_mul_f32 v[166:167], v[126:127], s[30:31]
	v_pk_mul_f32 v[120:121], v[104:105], v[120:121]
	v_pk_mul_f32 v[122:123], v[106:107], v[122:123]
	v_pk_mul_f32 v[124:125], v[108:109], v[124:125]
	v_pk_mul_f32 v[126:127], v[110:111], v[126:127]
	v_exp_f32_e32 v152, v152
	v_exp_f32_e32 v153, v153
	v_exp_f32_e32 v154, v154
	v_exp_f32_e32 v155, v155
	v_exp_f32_e32 v164, v164
	v_exp_f32_e32 v165, v165
	v_exp_f32_e32 v166, v166
	v_exp_f32_e32 v167, v167
	v_pk_add_f32 v[152:153], v[152:153], 1.0 op_sel_hi:[1,0]
	v_pk_add_f32 v[154:155], v[154:155], 1.0 op_sel_hi:[1,0]
	v_pk_add_f32 v[164:165], v[164:165], 1.0 op_sel_hi:[1,0]
	v_pk_add_f32 v[166:167], v[166:167], 1.0 op_sel_hi:[1,0]
	v_rcp_f32_e32 v152, v152
	v_rcp_f32_e32 v153, v153
	v_rcp_f32_e32 v154, v154
	v_rcp_f32_e32 v155, v155
	v_rcp_f32_e32 v164, v164
	v_rcp_f32_e32 v165, v165
	v_rcp_f32_e32 v166, v166
	v_rcp_f32_e32 v167, v167
	v_pk_mul_f32 v[120:121], v[120:121], v[152:153]
	v_pk_mul_f32 v[122:123], v[122:123], v[154:155]
	v_pk_mul_f32 v[124:125], v[124:125], v[164:165]
	v_pk_mul_f32 v[126:127], v[126:127], v[166:167]
	v_cvt_pk_bf16_f32 v152, v120, v121
	v_cvt_pk_bf16_f32 v153, v122, v123
	v_cvt_pk_bf16_f32 v154, v124, v125
	v_cvt_pk_bf16_f32 v155, v126, v127
	global_store_dwordx4 v67, v[152:155], s[84:85] offset:0
	global_load_dwordx4 v[128:131], v64, s[6:7] offset:256
	global_load_dwordx4 v[132:135], v64, s[6:7] offset:272
	global_load_dwordx4 v[136:139], v64, s[14:15] offset:256
	global_load_dwordx4 v[140:143], v64, s[14:15] offset:272
	global_load_dwordx4 v[144:147], v64, s[18:19] offset:256
	global_load_dwordx4 v[148:151], v64, s[18:19] offset:272
	s_barrier
; DI void stf8(float* p, const F8& f) { *(float4*)p = make_float4(f.v[0], f.v[1], f.v[2], f.v[3]); *(float4*)(p + 4) = make_float4(f.v[4], f.v[5], f.v[6], f.v[7]); }
; DI void stb8(bf16_t* p, const F8& f) { *(uint4*)p = pack8(f); }
; DI float siluf(float x) { return x / (1.f + __expf(-x)); }
; template <int MODE>
; DI void gemm_epilogue(const float* Cs, int m0, int n0, const Epi& ep) {
;     ...
;         const int mt = m0 >> 7, ch0 = (n0 >> 7) * 64, c8 = (tid & 7) * 8, ch = ch0 + c8;
;         const float* cw = ep.c0;
;         const F8 w0 = ldf8(cw + ch), w1 = ldf8(cw + 2816 + ch), w2 = ldf8(cw + 2 * 2816 + ch);
;         const bool defer01 = (m0 < MP) && ((m0 & 8191) != 0);
; #pragma unroll
;         for (int it = 0; it < 2; ++it) {
;             const int i = (tid >> 3) + 64 * it, r = m0 + i;
;             int sq, pos, len; rowinfo(r, sq, pos, len);
;             const F8 g0 = ldf8(Cs + i * LDC + c8), up = ldf8(Cs + i * LDC + 64 + c8);
;             if (i >= 126) stf8(ep.f0 + ((size_t)mt * 2 + (i - 126)) * 2816 + ch, g0);
;             if (i < 2) { stf8(ep.f1 + ((size_t)mt * 2 + i) * 2816 + ch, g0); stf8(ep.f2 + ((size_t)mt * 2 + i) * 2816 + ch, up); }
;             if (pos >= len - 2) {
;                 float* so = sq < 4 ? ep.out + O_PFF + (((size_t)ep.layer * 4 + sq) * 2 + (pos - (len - 2))) * 2816
;                                    : ep.out + O_SFF + (((size_t)ep.layer * 8 + (sq - 4)) * 2 + (pos - (len - 2))) * 2816;
;                 stf8(so + ch, g0);
;             }
;             if (i < 2 && defer01) continue;
;             F8 g1, g2;
;             const float* hist = sq >= 4 ? ep.c1 + ((size_t)ep.layer * 8 + (sq - 4)) * 2 * 2816 + ch : nullptr;
;             if (pos >= 1) g1 = ldf8(Cs + (i - 1) * LDC + c8);
;             else if (hist) g1 = ldf8(hist + 2816);
;             else { for (int e = 0; e < 8; ++e) g1.v[e] = 0.f; }
;             if (pos >= 2) g2 = ldf8(Cs + (i - 2) * LDC + c8);
;             else if (hist) g2 = ldf8(hist + (size_t)pos * 2816);
;             else { for (int e = 0; e < 8; ++e) g2.v[e] = 0.f; }
;             F8 o;
; #pragma unroll
;             for (int e = 0; e < 8; ++e) o.v[e] = siluf(w0.v[e] * g2.v[e] + w1.v[e] * g1.v[e] + w2.v[e] * g0.v[e]) * up.v[e];
;             stb8(ep.b0 + (size_t)r * 2816 + ch, o);
	ds_write_b128 v156, v[222:225]
	ds_write_b128 v156, v[68:71] offset:64
	ds_write_b128 v156, v[72:75] offset:8448
	ds_write_b128 v156, v[76:79] offset:8512
	ds_write_b128 v156, v[80:83] offset:16896
	ds_write_b128 v156, v[84:87] offset:16960
	ds_write_b128 v156, v[88:91] offset:25344
	ds_write_b128 v156, v[92:95] offset:25408
	s_waitcnt lgkmcnt(0)
	s_barrier
	ds_read_b128 v[96:99], v158
	ds_read_b128 v[100:103], v158 offset:16
	ds_read_b128 v[104:107], v158 offset:256
	ds_read_b128 v[108:111], v158 offset:272
	ds_read_b128 v[112:115], v157 offset:528
	ds_read_b128 v[116:119], v157 offset:544
	ds_read_b128 v[120:123], v157
	ds_read_b128 v[124:127], v157 offset:16
	s_waitcnt vmcnt(0)
	s_mov_b64 exec, s[42:43]
	s_cbranch_execz .Lffn_f3
	s_waitcnt lgkmcnt(4)
	global_store_dwordx4 v66, v[96:99], s[80:81] offset:256
	global_store_dwordx4 v66, v[100:103], s[80:81] offset:272
	global_store_dwordx4 v66, v[104:107], s[82:83] offset:256
	global_store_dwordx4 v66, v[108:111], s[82:83] offset:272
.Lffn_f3:
	s_mov_b64 exec, -1
	s_waitcnt lgkmcnt(0)
	v_pk_mul_f32 v[120:121], v[128:129], v[120:121]
	v_pk_mul_f32 v[122:123], v[130:131], v[122:123]
	v_pk_mul_f32 v[124:125], v[132:133], v[124:125]
	v_pk_mul_f32 v[126:127], v[134:135], v[126:127]
	v_pk_fma_f32 v[120:121], v[136:137], v[112:113], v[120:121]
	v_pk_fma_f32 v[122:123], v[138:139], v[114:115], v[122:123]
	v_pk_fma_f32 v[124:125], v[140:141], v[116:117], v[124:125]
	v_pk_fma_f32 v[126:127], v[142:143], v[118:119], v[126:127]
	v_pk_fma_f32 v[120:121], v[144:145], v[96:97], v[120:121]
	v_pk_fma_f32 v[122:123], v[146:147], v[98:99], v[122:123]
	v_pk_fma_f32 v[124:125], v[148:149], v[100:101], v[124:125]
	v_pk_fma_f32 v[126:127], v[150:151], v[102:103], v[126:127]
	v_pk_mul_f32 v[152:153], v[120:121], s[30:31]
	v_pk_mul_f32 v[154:155], v[122:123], s[30:31]
	v_pk_mul_f32 v[164:165], v[124:125], s[30:31]
	v_pk_mul_f32 v[166:167], v[126:127], s[30:31]
	v_pk_mul_f32 v[120:121], v[104:105], v[120:121]
	v_pk_mul_f32 v[122:123], v[106:107], v[122:123]
	v_pk_mul_f32 v[124:125], v[108:109], v[124:125]
	v_pk_mul_f32 v[126:127], v[110:111], v[126:127]
	v_exp_f32_e32 v152, v152
	v_exp_f32_e32 v153, v153
	v_exp_f32_e32 v154, v154
	v_exp_f32_e32 v155, v155
	v_exp_f32_e32 v164, v164
	v_exp_f32_e32 v165, v165
	v_exp_f32_e32 v166, v166
	v_exp_f32_e32 v167, v167
	v_pk_add_f32 v[152:153], v[152:153], 1.0 op_sel_hi:[1,0]
	v_pk_add_f32 v[154:155], v[154:155], 1.0 op_sel_hi:[1,0]
	v_pk_add_f32 v[164:165], v[164:165], 1.0 op_sel_hi:[1,0]
	v_pk_add_f32 v[166:167], v[166:167], 1.0 op_sel_hi:[1,0]
	v_rcp_f32_e32 v152, v152
	v_rcp_f32_e32 v153, v153
	v_rcp_f32_e32 v154, v154
	v_rcp_f32_e32 v155, v155
	v_rcp_f32_e32 v164, v164
	v_rcp_f32_e32 v165, v165
	v_rcp_f32_e32 v166, v166
	v_rcp_f32_e32 v167, v167
	v_pk_mul_f32 v[120:121], v[120:121], v[152:153]
	v_pk_mul_f32 v[122:123], v[122:123], v[154:155]
	v_pk_mul_f32 v[124:125], v[124:125], v[164:165]
	v_pk_mul_f32 v[126:127], v[126:127], v[166:167]
	v_cvt_pk_bf16_f32 v152, v120, v121
	v_cvt_pk_bf16_f32 v153, v122, v123
	v_cvt_pk_bf16_f32 v154, v124, v125
	v_cvt_pk_bf16_f32 v155, v126, v127
	s_mov_b64 exec, s[40:41]
	global_store_dwordx4 v65, v[152:155], s[84:85] offset:128
	s_mov_b64 exec, -1
	ds_read_b128 v[96:99], v158 offset:33792
	ds_read_b128 v[100:103], v158 offset:33808
	ds_read_b128 v[104:107], v158 offset:34048
	ds_read_b128 v[108:111], v158 offset:34064
	ds_read_b128 v[112:115], v158 offset:33264
	ds_read_b128 v[116:119], v158 offset:33280
	ds_read_b128 v[120:123], v158 offset:32736
	ds_read_b128 v[124:127], v158 offset:32752
	v_add_u32_e32 v67, 0x58000, v65
	s_mov_b64 exec, s[44:45]
	s_cbranch_execz .Lffn_f4
	v_add_u32_e32 v212, 0xfff55800, v66
	s_waitcnt lgkmcnt(6)
	global_store_dwordx4 v212, v[96:99], s[72:73] offset:256
	global_store_dwordx4 v212, v[100:103], s[72:73] offset:272
.Lffn_f4:
	s_mov_b64 exec, -1
	s_waitcnt lgkmcnt(0)
	v_pk_mul_f32 v[120:121], v[128:129], v[120:121]
	v_pk_mul_f32 v[122:123], v[130:131], v[122:123]
	v_pk_mul_f32 v[124:125], v[132:133], v[124:125]
	v_pk_mul_f32 v[126:127], v[134:135], v[126:127]
	v_pk_fma_f32 v[120:121], v[136:137], v[112:113], v[120:121]
	v_pk_fma_f32 v[122:123], v[138:139], v[114:115], v[122:123]
	v_pk_fma_f32 v[124:125], v[140:141], v[116:117], v[124:125]
	v_pk_fma_f32 v[126:127], v[142:143], v[118:119], v[126:127]
	v_pk_fma_f32 v[120:121], v[144:145], v[96:97], v[120:121]
	v_pk_fma_f32 v[122:123], v[146:147], v[98:99], v[122:123]
	v_pk_fma_f32 v[124:125], v[148:149], v[100:101], v[124:125]
	v_pk_fma_f32 v[126:127], v[150:151], v[102:103], v[126:127]
	v_pk_mul_f32 v[152:153], v[120:121], s[30:31]
	v_pk_mul_f32 v[154:155], v[122:123], s[30:31]
	v_pk_mul_f32 v[164:165], v[124:125], s[30:31]
	v_pk_mul_f32 v[166:167], v[126:127], s[30:31]
	v_pk_mul_f32 v[120:121], v[104:105], v[120:121]
	v_pk_mul_f32 v[122:123], v[106:107], v[122:123]
	v_pk_mul_f32 v[124:125], v[108:109], v[124:125]
	v_pk_mul_f32 v[126:127], v[110:111], v[126:127]
	v_exp_f32_e32 v152, v152
	v_exp_f32_e32 v153, v153
	v_exp_f32_e32 v154, v154
	v_exp_f32_e32 v155, v155
	v_exp_f32_e32 v164, v164
	v_exp_f32_e32 v165, v165
	v_exp_f32_e32 v166, v166
	v_exp_f32_e32 v167, v167
	v_pk_add_f32 v[152:153], v[152:153], 1.0 op_sel_hi:[1,0]
	v_pk_add_f32 v[154:155], v[154:155], 1.0 op_sel_hi:[1,0]
	v_pk_add_f32 v[164:165], v[164:165], 1.0 op_sel_hi:[1,0]
	v_pk_add_f32 v[166:167], v[166:167], 1.0 op_sel_hi:[1,0]
	v_rcp_f32_e32 v152, v152
	v_rcp_f32_e32 v153, v153
	v_rcp_f32_e32 v154, v154
	v_rcp_f32_e32 v155, v155
	v_rcp_f32_e32 v164, v164
	v_rcp_f32_e32 v165, v165
	v_rcp_f32_e32 v166, v166
	v_rcp_f32_e32 v167, v167
	v_pk_mul_f32 v[120:121], v[120:121], v[152:153]
	v_pk_mul_f32 v[122:123], v[122:123], v[154:155]
	v_pk_mul_f32 v[124:125], v[124:125], v[164:165]
	v_pk_mul_f32 v[126:127], v[126:127], v[166:167]
	v_cvt_pk_bf16_f32 v152, v120, v121
	v_cvt_pk_bf16_f32 v153, v122, v123
	v_cvt_pk_bf16_f32 v154, v124, v125
	v_cvt_pk_bf16_f32 v155, v126, v127
	global_store_dwordx4 v67, v[152:155], s[84:85] offset:128
	global_load_dwordx4 v[128:131], v64, s[6:7] offset:0
	global_load_dwordx4 v[132:135], v64, s[6:7] offset:16
	global_load_dwordx4 v[136:139], v64, s[14:15] offset:0
	global_load_dwordx4 v[140:143], v64, s[14:15] offset:16
	global_load_dwordx4 v[144:147], v64, s[18:19] offset:0
	global_load_dwordx4 v[148:151], v64, s[18:19] offset:16
	s_barrier
; DI void stf8(float* p, const F8& f) { *(float4*)p = make_float4(f.v[0], f.v[1], f.v[2], f.v[3]); *(float4*)(p + 4) = make_float4(f.v[4], f.v[5], f.v[6], f.v[7]); }
; DI void stb8(bf16_t* p, const F8& f) { *(uint4*)p = pack8(f); }
; DI float siluf(float x) { return x / (1.f + __expf(-x)); }
; template <int MODE>
; DI void gemm_epilogue(const float* Cs, int m0, int n0, const Epi& ep) {
;     ...
;         const int mt = m0 >> 7, ch0 = (n0 >> 7) * 64, c8 = (tid & 7) * 8, ch = ch0 + c8;
;         const float* cw = ep.c0;
;         const F8 w0 = ldf8(cw + ch), w1 = ldf8(cw + 2816 + ch), w2 = ldf8(cw + 2 * 2816 + ch);
;         const bool defer01 = (m0 < MP) && ((m0 & 8191) != 0);
; #pragma unroll
;         for (int it = 0; it < 2; ++it) {
;             const int i = (tid >> 3) + 64 * it, r = m0 + i;
;             int sq, pos, len; rowinfo(r, sq, pos, len);
;             const F8 g0 = ldf8(Cs + i * LDC + c8), up = ldf8(Cs + i * LDC + 64 + c8);
;             if (i >= 126) stf8(ep.f0 + ((size_t)mt * 2 + (i - 126)) * 2816 + ch, g0);
;             if (i < 2) { stf8(ep.f1 + ((size_t)mt * 2 + i) * 2816 + ch, g0); stf8(ep.f2 + ((size_t)mt * 2 + i) * 2816 + ch, up); }
;             if (pos >= len - 2) {
;                 float* so = sq < 4 ? ep.out + O_PFF + (((size_t)ep.layer * 4 + sq) * 2 + (pos - (len - 2))) * 2816
;                                    : ep.out + O_SFF + (((size_t)ep.layer * 8 + (sq - 4)) * 2 + (pos - (len - 2))) * 2816;
;                 stf8(so + ch, g0);
;             }
;             if (i < 2 && defer01) continue;
;             F8 g1, g2;
;             const float* hist = sq >= 4 ? ep.c1 + ((size_t)ep.layer * 8 + (sq - 4)) * 2 * 2816 + ch : nullptr;
;             if (pos >= 1) g1 = ldf8(Cs + (i - 1) * LDC + c8);
;             else if (hist) g1 = ldf8(hist + 2816);
;             else { for (int e = 0; e < 8; ++e) g1.v[e] = 0.f; }
;             if (pos >= 2) g2 = ldf8(Cs + (i - 2) * LDC + c8);
;             else if (hist) g2 = ldf8(hist + (size_t)pos * 2816);
;             else { for (int e = 0; e < 8; ++e) g2.v[e] = 0.f; }
;             F8 o;
; #pragma unroll
;             for (int e = 0; e < 8; ++e) o.v[e] = siluf(w0.v[e] * g2.v[e] + w1.v[e] * g1.v[e] + w2.v[e] * g0.v[e]) * up.v[e];
;             stb8(ep.b0 + (size_t)r * 2816 + ch, o);
	ds_write_b128 v156, v[32:35]
	ds_write_b128 v156, v[36:39] offset:64
	ds_write_b128 v156, v[40:43] offset:8448
	ds_write_b128 v156, v[44:47] offset:8512
	ds_write_b128 v156, v[48:51] offset:16896
	ds_write_b128 v156, v[52:55] offset:16960
	ds_write_b128 v156, v[56:59] offset:25344
	ds_write_b128 v156, v[60:63] offset:25408
	s_waitcnt lgkmcnt(0)
	s_barrier
	ds_read_b128 v[96:99], v158
	ds_read_b128 v[100:103], v158 offset:16
	ds_read_b128 v[104:107], v158 offset:256
	ds_read_b128 v[108:111], v158 offset:272
	ds_read_b128 v[112:115], v157 offset:528
	ds_read_b128 v[116:119], v157 offset:544
	ds_read_b128 v[120:123], v157
	ds_read_b128 v[124:127], v157 offset:16
	v_add_u32_e32 v67, 0xb0000, v65
	s_waitcnt vmcnt(0)
	s_mov_b64 exec, s[42:43]
	s_cbranch_execz .Lffn_f5
	v_add_u32_e32 v212, 0x5800, v66
	s_waitcnt lgkmcnt(4)
	global_store_dwordx4 v212, v[96:99], s[80:81] offset:0
	global_store_dwordx4 v212, v[100:103], s[80:81] offset:16
	global_store_dwordx4 v212, v[104:107], s[82:83] offset:0
	global_store_dwordx4 v212, v[108:111], s[82:83] offset:16
.Lffn_f5:
	s_mov_b64 exec, -1
	s_waitcnt lgkmcnt(0)
	v_pk_mul_f32 v[120:121], v[128:129], v[120:121]
	v_pk_mul_f32 v[122:123], v[130:131], v[122:123]
	v_pk_mul_f32 v[124:125], v[132:133], v[124:125]
	v_pk_mul_f32 v[126:127], v[134:135], v[126:127]
	v_pk_fma_f32 v[120:121], v[136:137], v[112:113], v[120:121]
	v_pk_fma_f32 v[122:123], v[138:139], v[114:115], v[122:123]
	v_pk_fma_f32 v[124:125], v[140:141], v[116:117], v[124:125]
	v_pk_fma_f32 v[126:127], v[142:143], v[118:119], v[126:127]
	v_pk_fma_f32 v[120:121], v[144:145], v[96:97], v[120:121]
	v_pk_fma_f32 v[122:123], v[146:147], v[98:99], v[122:123]
	v_pk_fma_f32 v[124:125], v[148:149], v[100:101], v[124:125]
	v_pk_fma_f32 v[126:127], v[150:151], v[102:103], v[126:127]
	v_pk_mul_f32 v[152:153], v[120:121], s[30:31]
	v_pk_mul_f32 v[154:155], v[122:123], s[30:31]
	v_pk_mul_f32 v[164:165], v[124:125], s[30:31]
	v_pk_mul_f32 v[166:167], v[126:127], s[30:31]
	v_pk_mul_f32 v[120:121], v[104:105], v[120:121]
	v_pk_mul_f32 v[122:123], v[106:107], v[122:123]
	v_pk_mul_f32 v[124:125], v[108:109], v[124:125]
	v_pk_mul_f32 v[126:127], v[110:111], v[126:127]
	v_exp_f32_e32 v152, v152
	v_exp_f32_e32 v153, v153
	v_exp_f32_e32 v154, v154
	v_exp_f32_e32 v155, v155
	v_exp_f32_e32 v164, v164
	v_exp_f32_e32 v165, v165
	v_exp_f32_e32 v166, v166
	v_exp_f32_e32 v167, v167
	v_pk_add_f32 v[152:153], v[152:153], 1.0 op_sel_hi:[1,0]
	v_pk_add_f32 v[154:155], v[154:155], 1.0 op_sel_hi:[1,0]
	v_pk_add_f32 v[164:165], v[164:165], 1.0 op_sel_hi:[1,0]
	v_pk_add_f32 v[166:167], v[166:167], 1.0 op_sel_hi:[1,0]
	v_rcp_f32_e32 v152, v152
	v_rcp_f32_e32 v153, v153
	v_rcp_f32_e32 v154, v154
	v_rcp_f32_e32 v155, v155
	v_rcp_f32_e32 v164, v164
	v_rcp_f32_e32 v165, v165
	v_rcp_f32_e32 v166, v166
	v_rcp_f32_e32 v167, v167
	v_pk_mul_f32 v[120:121], v[120:121], v[152:153]
	v_pk_mul_f32 v[122:123], v[122:123], v[154:155]
	v_pk_mul_f32 v[124:125], v[124:125], v[164:165]
	v_pk_mul_f32 v[126:127], v[126:127], v[166:167]
	v_cvt_pk_bf16_f32 v152, v120, v121
	v_cvt_pk_bf16_f32 v153, v122, v123
	v_cvt_pk_bf16_f32 v154, v124, v125
	v_cvt_pk_bf16_f32 v155, v126, v127
	s_mov_b64 exec, s[40:41]
	global_store_dwordx4 v67, v[152:155], s[84:85] offset:0
	s_mov_b64 exec, -1
	ds_read_b128 v[96:99], v158 offset:33792
	ds_read_b128 v[100:103], v158 offset:33808
	ds_read_b128 v[104:107], v158 offset:34048
	ds_read_b128 v[108:111], v158 offset:34064
	ds_read_b128 v[112:115], v158 offset:33264
	ds_read_b128 v[116:119], v158 offset:33280
	ds_read_b128 v[120:123], v158 offset:32736
	ds_read_b128 v[124:127], v158 offset:32752
	v_add_u32_e32 v67, 0x108000, v65
	s_mov_b64 exec, s[44:45]
	s_cbranch_execz .Lffn_f6
	v_add_u32_e32 v212, 0xfff5b000, v66
	s_waitcnt lgkmcnt(6)
	global_store_dwordx4 v212, v[96:99], s[72:73] offset:0
	global_store_dwordx4 v212, v[100:103], s[72:73] offset:16
; DI void stf8(float* p, const F8& f) { *(float4*)p = make_float4(f.v[0], f.v[1], f.v[2], f.v[3]); *(float4*)(p + 4) = make_float4(f.v[4], f.v[5], f.v[6], f.v[7]); }
; DI void stb8(bf16_t* p, const F8& f) { *(uint4*)p = pack8(f); }
; DI float siluf(float x) { return x / (1.f + __expf(-x)); }
; template <int MODE>
; DI void gemm_epilogue(const float* Cs, int m0, int n0, const Epi& ep) {
;     ...
;         const int mt = m0 >> 7, ch0 = (n0 >> 7) * 64, c8 = (tid & 7) * 8, ch = ch0 + c8;
;         const float* cw = ep.c0;
;         const F8 w0 = ldf8(cw + ch), w1 = ldf8(cw + 2816 + ch), w2 = ldf8(cw + 2 * 2816 + ch);
;         const bool defer01 = (m0 < MP) && ((m0 & 8191) != 0);
; #pragma unroll
;         for (int it = 0; it < 2; ++it) {
;             const int i = (tid >> 3) + 64 * it, r = m0 + i;
;             int sq, pos, len; rowinfo(r, sq, pos, len);
;             const F8 g0 = ldf8(Cs + i * LDC + c8), up = ldf8(Cs + i * LDC + 64 + c8);
;             if (i >= 126) stf8(ep.f0 + ((size_t)mt * 2 + (i - 126)) * 2816 + ch, g0);
;             if (i < 2) { stf8(ep.f1 + ((size_t)mt * 2 + i) * 2816 + ch, g0); stf8(ep.f2 + ((size_t)mt * 2 + i) * 2816 + ch, up); }
;             if (pos >= len - 2) {
;                 float* so = sq < 4 ? ep.out + O_PFF + (((size_t)ep.layer * 4 + sq) * 2 + (pos - (len - 2))) * 2816
;                                    : ep.out + O_SFF + (((size_t)ep.layer * 8 + (sq - 4)) * 2 + (pos - (len - 2))) * 2816;
;                 stf8(so + ch, g0);
;             }
;             if (i < 2 && defer01) continue;
;             F8 g1, g2;
;             const float* hist = sq >= 4 ? ep.c1 + ((size_t)ep.layer * 8 + (sq - 4)) * 2 * 2816 + ch : nullptr;
;             if (pos >= 1) g1 = ldf8(Cs + (i - 1) * LDC + c8);
;             else if (hist) g1 = ldf8(hist + 2816);
;             else { for (int e = 0; e < 8; ++e) g1.v[e] = 0.f; }
;             if (pos >= 2) g2 = ldf8(Cs + (i - 2) * LDC + c8);
;             else if (hist) g2 = ldf8(hist + (size_t)pos * 2816);
;             else { for (int e = 0; e < 8; ++e) g2.v[e] = 0.f; }
;             F8 o;
; #pragma unroll
;             for (int e = 0; e < 8; ++e) o.v[e] = siluf(w0.v[e] * g2.v[e] + w1.v[e] * g1.v[e] + w2.v[e] * g0.v[e]) * up.v[e];
;             stb8(ep.b0 + (size_t)r * 2816 + ch, o);
.Lffn_f6:
	s_mov_b64 exec, -1
	s_waitcnt lgkmcnt(0)
	v_pk_mul_f32 v[120:121], v[128:129], v[120:121]
	v_pk_mul_f32 v[122:123], v[130:131], v[122:123]
	v_pk_mul_f32 v[124:125], v[132:133], v[124:125]
	v_pk_mul_f32 v[126:127], v[134:135], v[126:127]
	v_pk_fma_f32 v[120:121], v[136:137], v[112:113], v[120:121]
	v_pk_fma_f32 v[122:123], v[138:139], v[114:115], v[122:123]
	v_pk_fma_f32 v[124:125], v[140:141], v[116:117], v[124:125]
	v_pk_fma_f32 v[126:127], v[142:143], v[118:119], v[126:127]
	v_pk_fma_f32 v[120:121], v[144:145], v[96:97], v[120:121]
	v_pk_fma_f32 v[122:123], v[146:147], v[98:99], v[122:123]
	v_pk_fma_f32 v[124:125], v[148:149], v[100:101], v[124:125]
	v_pk_fma_f32 v[126:127], v[150:151], v[102:103], v[126:127]
	v_pk_mul_f32 v[152:153], v[120:121], s[30:31]
	v_pk_mul_f32 v[154:155], v[122:123], s[30:31]
	v_pk_mul_f32 v[164:165], v[124:125], s[30:31]
	v_pk_mul_f32 v[166:167], v[126:127], s[30:31]
	v_pk_mul_f32 v[120:121], v[104:105], v[120:121]
	v_pk_mul_f32 v[122:123], v[106:107], v[122:123]
	v_pk_mul_f32 v[124:125], v[108:109], v[124:125]
	v_pk_mul_f32 v[126:127], v[110:111], v[126:127]
	v_exp_f32_e32 v152, v152
	v_exp_f32_e32 v153, v153
	v_exp_f32_e32 v154, v154
	v_exp_f32_e32 v155, v155
	v_exp_f32_e32 v164, v164
	v_exp_f32_e32 v165, v165
	v_exp_f32_e32 v166, v166
	v_exp_f32_e32 v167, v167
	v_pk_add_f32 v[152:153], v[152:153], 1.0 op_sel_hi:[1,0]
	v_pk_add_f32 v[154:155], v[154:155], 1.0 op_sel_hi:[1,0]
	v_pk_add_f32 v[164:165], v[164:165], 1.0 op_sel_hi:[1,0]
	v_pk_add_f32 v[166:167], v[166:167], 1.0 op_sel_hi:[1,0]
	v_rcp_f32_e32 v152, v152
	v_rcp_f32_e32 v153, v153
	v_rcp_f32_e32 v154, v154
	v_rcp_f32_e32 v155, v155
	v_rcp_f32_e32 v164, v164
	v_rcp_f32_e32 v165, v165
	v_rcp_f32_e32 v166, v166
	v_rcp_f32_e32 v167, v167
	v_pk_mul_f32 v[120:121], v[120:121], v[152:153]
	v_pk_mul_f32 v[122:123], v[122:123], v[154:155]
	v_pk_mul_f32 v[124:125], v[124:125], v[164:165]
	v_pk_mul_f32 v[126:127], v[126:127], v[166:167]
	v_cvt_pk_bf16_f32 v152, v120, v121
	v_cvt_pk_bf16_f32 v153, v122, v123
	v_cvt_pk_bf16_f32 v154, v124, v125
	v_cvt_pk_bf16_f32 v155, v126, v127
	global_store_dwordx4 v67, v[152:155], s[84:85] offset:0
	global_load_dwordx4 v[128:131], v64, s[6:7] offset:256
	global_load_dwordx4 v[132:135], v64, s[6:7] offset:272
	global_load_dwordx4 v[136:139], v64, s[14:15] offset:256
	global_load_dwordx4 v[140:143], v64, s[14:15] offset:272
	global_load_dwordx4 v[144:147], v64, s[18:19] offset:256
	global_load_dwordx4 v[148:151], v64, s[18:19] offset:272
	s_barrier
	ds_write_b128 v156, v[0:3]
	ds_write_b128 v156, v[4:7] offset:64
	ds_write_b128 v156, v[8:11] offset:8448
	ds_write_b128 v156, v[12:15] offset:8512
	ds_write_b128 v156, v[16:19] offset:16896
	ds_write_b128 v156, v[20:23] offset:16960
	ds_write_b128 v156, v[24:27] offset:25344
	ds_write_b128 v156, v[28:31] offset:25408
	s_waitcnt lgkmcnt(0)
	s_barrier
	ds_read_b128 v[96:99], v158
	ds_read_b128 v[100:103], v158 offset:16
	ds_read_b128 v[104:107], v158 offset:256
	ds_read_b128 v[108:111], v158 offset:272
	ds_read_b128 v[112:115], v157 offset:528
	ds_read_b128 v[116:119], v157 offset:544
	ds_read_b128 v[120:123], v157
	ds_read_b128 v[124:127], v157 offset:16
	v_add_u32_e32 v67, 0xb0000, v65
	s_waitcnt vmcnt(0)
	s_mov_b64 exec, s[42:43]
	s_cbranch_execz .Lffn_f7
	v_add_u32_e32 v212, 0x5800, v66
	s_waitcnt lgkmcnt(4)
	global_store_dwordx4 v212, v[96:99], s[80:81] offset:256
	global_store_dwordx4 v212, v[100:103], s[80:81] offset:272
	global_store_dwordx4 v212, v[104:107], s[82:83] offset:256
	global_store_dwordx4 v212, v[108:111], s[82:83] offset:272
.Lffn_f7:
	s_mov_b64 exec, -1
	s_waitcnt lgkmcnt(0)
	v_pk_mul_f32 v[120:121], v[128:129], v[120:121]
	v_pk_mul_f32 v[122:123], v[130:131], v[122:123]
	v_pk_mul_f32 v[124:125], v[132:133], v[124:125]
	v_pk_mul_f32 v[126:127], v[134:135], v[126:127]
	v_pk_fma_f32 v[120:121], v[136:137], v[112:113], v[120:121]
	v_pk_fma_f32 v[122:123], v[138:139], v[114:115], v[122:123]
	v_pk_fma_f32 v[124:125], v[140:141], v[116:117], v[124:125]
	v_pk_fma_f32 v[126:127], v[142:143], v[118:119], v[126:127]
	v_pk_fma_f32 v[120:121], v[144:145], v[96:97], v[120:121]
	v_pk_fma_f32 v[122:123], v[146:147], v[98:99], v[122:123]
	v_pk_fma_f32 v[124:125], v[148:149], v[100:101], v[124:125]
	v_pk_fma_f32 v[126:127], v[150:151], v[102:103], v[126:127]
	v_pk_mul_f32 v[152:153], v[120:121], s[30:31]
	v_pk_mul_f32 v[154:155], v[122:123], s[30:31]
	v_pk_mul_f32 v[164:165], v[124:125], s[30:31]
	v_pk_mul_f32 v[166:167], v[126:127], s[30:31]
	v_pk_mul_f32 v[120:121], v[104:105], v[120:121]
	v_pk_mul_f32 v[122:123], v[106:107], v[122:123]
	v_pk_mul_f32 v[124:125], v[108:109], v[124:125]
	v_pk_mul_f32 v[126:127], v[110:111], v[126:127]
	v_exp_f32_e32 v152, v152
	v_exp_f32_e32 v153, v153
	v_exp_f32_e32 v154, v154
	v_exp_f32_e32 v155, v155
	v_exp_f32_e32 v164, v164
	v_exp_f32_e32 v165, v165
	v_exp_f32_e32 v166, v166
	v_exp_f32_e32 v167, v167
	v_pk_add_f32 v[152:153], v[152:153], 1.0 op_sel_hi:[1,0]
	v_pk_add_f32 v[154:155], v[154:155], 1.0 op_sel_hi:[1,0]
	v_pk_add_f32 v[164:165], v[164:165], 1.0 op_sel_hi:[1,0]
	v_pk_add_f32 v[166:167], v[166:167], 1.0 op_sel_hi:[1,0]
	v_rcp_f32_e32 v152, v152
	v_rcp_f32_e32 v153, v153
	v_rcp_f32_e32 v154, v154
	v_rcp_f32_e32 v155, v155
	v_rcp_f32_e32 v164, v164
	v_rcp_f32_e32 v165, v165
	v_rcp_f32_e32 v166, v166
	v_rcp_f32_e32 v167, v167
	v_pk_mul_f32 v[120:121], v[120:121], v[152:153]
	v_pk_mul_f32 v[122:123], v[122:123], v[154:155]
	v_pk_mul_f32 v[124:125], v[124:125], v[164:165]
	v_pk_mul_f32 v[126:127], v[126:127], v[166:167]
	v_cvt_pk_bf16_f32 v152, v120, v121
	v_cvt_pk_bf16_f32 v153, v122, v123
	v_cvt_pk_bf16_f32 v154, v124, v125
	v_cvt_pk_bf16_f32 v155, v126, v127
	s_mov_b64 exec, s[40:41]
	global_store_dwordx4 v67, v[152:155], s[84:85] offset:128
	s_mov_b64 exec, -1
	ds_read_b128 v[96:99], v158 offset:33792
	ds_read_b128 v[100:103], v158 offset:33808
	ds_read_b128 v[104:107], v158 offset:34048
	ds_read_b128 v[108:111], v158 offset:34064
	ds_read_b128 v[112:115], v158 offset:33264
	ds_read_b128 v[116:119], v158 offset:33280
	ds_read_b128 v[120:123], v158 offset:32736
	ds_read_b128 v[124:127], v158 offset:32752
	v_add_u32_e32 v67, 0x108000, v65
	s_mov_b64 exec, s[44:45]
	s_cbranch_execz .Lffn_f8
	v_add_u32_e32 v212, 0xfff5b000, v66
	s_waitcnt lgkmcnt(6)
	global_store_dwordx4 v212, v[96:99], s[72:73] offset:256
	global_store_dwordx4 v212, v[100:103], s[72:73] offset:272
